# P5 QK-norm+rope loop hand-rewritten (DPP wave sums, v_rsq, next-row prefetch); P3 gate-code weight staging with 64 loads in flight and DPP reductions in the bz loop
# speedup vs baseline: 1.0108x; 1.0067x over previous
; #define LAS __attribute__((address_space(3)))
; __global__ void __launch_bounds__(NWAVES * 64, 2) fwd_megakernel(Args args) {
;     ...
;         LAS float* wz = (LAS float*)F.lds;
;         const float* w_in = args.in[7];
;         for (int e = F.tid; e < D * 16; e += NWAVES * 64) { const int k = e >> 4, j = e & 15; wz[j * D + k] = w_in[(size_t)k * 10256 + 6144 + j]; }
.LBB0_187:
	s_or_b64 exec, exec, s[0:1]
	v_lshrrev_b32_e32 v7, 9, v136
	s_waitcnt lgkmcnt(0)
	v_sub_u32_e32 v0, 62, v7
	v_and_b32_e32 v132, 15, v136
	v_lshrrev_b32_e32 v0, 1, v0
	v_mov_b32_e32 v5, 0
	v_lshlrev_b32_e32 v6, 13, v132
	v_add_u32_e32 v9, 1, v0
	v_add_u32_e32 v137, 0x200, v136
	v_add_u32_e32 v8, 0, v6
	v_and_b32_e32 v10, 60, v9
	s_mov_b64 s[4:5], 0
	s_mov_b32 s6, 0xa040
	v_lshlrev_b32_e32 v0, 2, v132
	v_mov_b32_e32 v1, v5
	s_movk_i32 s7, 0x6000
	v_mov_b64_e32 v[2:3], v[136:137]
	s_barrier
	v_lshrrev_b32_e32 v10, 4, v136
	v_and_b32_e32 v11, 15, v136
	v_mov_b32_e32 v12, 0xa040
	v_mad_u64_u32 v[14:15], s[4:5], v10, v12, s[22:23]
	v_lshlrev_b32_e32 v16, 2, v11
	v_add_u32_e32 v16, 0x6000, v16
	v_mov_b32_e32 v17, 0
	v_lshl_add_u64 v[14:15], v[14:15], 0, v[16:17]
	s_mov_b32 s4, 0x140800
	s_mov_b32 s5, 0
	v_lshlrev_b32_e32 v18, 13, v11
	v_lshl_add_u32 v18, v10, 2, v18
	global_load_dword v20, v[14:15], off
	v_lshl_add_u64 v[14:15], v[14:15], 0, s[4:5]
	global_load_dword v21, v[14:15], off
	v_lshl_add_u64 v[14:15], v[14:15], 0, s[4:5]
	global_load_dword v22, v[14:15], off
	v_lshl_add_u64 v[14:15], v[14:15], 0, s[4:5]
	global_load_dword v23, v[14:15], off
	v_lshl_add_u64 v[14:15], v[14:15], 0, s[4:5]
	global_load_dword v24, v[14:15], off
	v_lshl_add_u64 v[14:15], v[14:15], 0, s[4:5]
	global_load_dword v25, v[14:15], off
	v_lshl_add_u64 v[14:15], v[14:15], 0, s[4:5]
	global_load_dword v26, v[14:15], off
	v_lshl_add_u64 v[14:15], v[14:15], 0, s[4:5]
	global_load_dword v27, v[14:15], off
	v_lshl_add_u64 v[14:15], v[14:15], 0, s[4:5]
	global_load_dword v28, v[14:15], off
	v_lshl_add_u64 v[14:15], v[14:15], 0, s[4:5]
	global_load_dword v29, v[14:15], off
	v_lshl_add_u64 v[14:15], v[14:15], 0, s[4:5]
	global_load_dword v30, v[14:15], off
	v_lshl_add_u64 v[14:15], v[14:15], 0, s[4:5]
	global_load_dword v31, v[14:15], off
	v_lshl_add_u64 v[14:15], v[14:15], 0, s[4:5]
	global_load_dword v32, v[14:15], off
	v_lshl_add_u64 v[14:15], v[14:15], 0, s[4:5]
	global_load_dword v33, v[14:15], off
	v_lshl_add_u64 v[14:15], v[14:15], 0, s[4:5]
	global_load_dword v34, v[14:15], off
	v_lshl_add_u64 v[14:15], v[14:15], 0, s[4:5]
	global_load_dword v35, v[14:15], off
	v_lshl_add_u64 v[14:15], v[14:15], 0, s[4:5]
	global_load_dword v36, v[14:15], off
	v_lshl_add_u64 v[14:15], v[14:15], 0, s[4:5]
	global_load_dword v37, v[14:15], off
	v_lshl_add_u64 v[14:15], v[14:15], 0, s[4:5]
	global_load_dword v38, v[14:15], off
	v_lshl_add_u64 v[14:15], v[14:15], 0, s[4:5]
	global_load_dword v39, v[14:15], off
	v_lshl_add_u64 v[14:15], v[14:15], 0, s[4:5]
	global_load_dword v40, v[14:15], off
	v_lshl_add_u64 v[14:15], v[14:15], 0, s[4:5]
	global_load_dword v41, v[14:15], off
	v_lshl_add_u64 v[14:15], v[14:15], 0, s[4:5]
	global_load_dword v42, v[14:15], off
	v_lshl_add_u64 v[14:15], v[14:15], 0, s[4:5]
	global_load_dword v43, v[14:15], off
	v_lshl_add_u64 v[14:15], v[14:15], 0, s[4:5]
	global_load_dword v44, v[14:15], off
	v_lshl_add_u64 v[14:15], v[14:15], 0, s[4:5]
	global_load_dword v45, v[14:15], off
	v_lshl_add_u64 v[14:15], v[14:15], 0, s[4:5]
	global_load_dword v46, v[14:15], off
	v_lshl_add_u64 v[14:15], v[14:15], 0, s[4:5]
	global_load_dword v47, v[14:15], off
	v_lshl_add_u64 v[14:15], v[14:15], 0, s[4:5]
	global_load_dword v48, v[14:15], off
	v_lshl_add_u64 v[14:15], v[14:15], 0, s[4:5]
	global_load_dword v49, v[14:15], off
	v_lshl_add_u64 v[14:15], v[14:15], 0, s[4:5]
	global_load_dword v50, v[14:15], off
	v_lshl_add_u64 v[14:15], v[14:15], 0, s[4:5]
	global_load_dword v51, v[14:15], off
	v_lshl_add_u64 v[14:15], v[14:15], 0, s[4:5]
	global_load_dword v52, v[14:15], off
	v_lshl_add_u64 v[14:15], v[14:15], 0, s[4:5]
	global_load_dword v53, v[14:15], off
	v_lshl_add_u64 v[14:15], v[14:15], 0, s[4:5]
	global_load_dword v54, v[14:15], off
	v_lshl_add_u64 v[14:15], v[14:15], 0, s[4:5]
	global_load_dword v55, v[14:15], off
	v_lshl_add_u64 v[14:15], v[14:15], 0, s[4:5]
	global_load_dword v56, v[14:15], off
	v_lshl_add_u64 v[14:15], v[14:15], 0, s[4:5]
	global_load_dword v57, v[14:15], off
	v_lshl_add_u64 v[14:15], v[14:15], 0, s[4:5]
	global_load_dword v58, v[14:15], off
	v_lshl_add_u64 v[14:15], v[14:15], 0, s[4:5]
	global_load_dword v59, v[14:15], off
	v_lshl_add_u64 v[14:15], v[14:15], 0, s[4:5]
	global_load_dword v60, v[14:15], off
	v_lshl_add_u64 v[14:15], v[14:15], 0, s[4:5]
	global_load_dword v61, v[14:15], off
	v_lshl_add_u64 v[14:15], v[14:15], 0, s[4:5]
	global_load_dword v62, v[14:15], off
	v_lshl_add_u64 v[14:15], v[14:15], 0, s[4:5]
	global_load_dword v63, v[14:15], off
	v_lshl_add_u64 v[14:15], v[14:15], 0, s[4:5]
	global_load_dword v64, v[14:15], off
	v_lshl_add_u64 v[14:15], v[14:15], 0, s[4:5]
	global_load_dword v65, v[14:15], off
	v_lshl_add_u64 v[14:15], v[14:15], 0, s[4:5]
	global_load_dword v66, v[14:15], off
	v_lshl_add_u64 v[14:15], v[14:15], 0, s[4:5]
	global_load_dword v67, v[14:15], off
	v_lshl_add_u64 v[14:15], v[14:15], 0, s[4:5]
	global_load_dword v68, v[14:15], off
	v_lshl_add_u64 v[14:15], v[14:15], 0, s[4:5]
	global_load_dword v69, v[14:15], off
	v_lshl_add_u64 v[14:15], v[14:15], 0, s[4:5]
	global_load_dword v70, v[14:15], off
	v_lshl_add_u64 v[14:15], v[14:15], 0, s[4:5]
	global_load_dword v71, v[14:15], off
	v_lshl_add_u64 v[14:15], v[14:15], 0, s[4:5]
	global_load_dword v72, v[14:15], off
	v_lshl_add_u64 v[14:15], v[14:15], 0, s[4:5]
	global_load_dword v73, v[14:15], off
	v_lshl_add_u64 v[14:15], v[14:15], 0, s[4:5]
	global_load_dword v74, v[14:15], off
	v_lshl_add_u64 v[14:15], v[14:15], 0, s[4:5]
	global_load_dword v75, v[14:15], off
	v_lshl_add_u64 v[14:15], v[14:15], 0, s[4:5]
	global_load_dword v76, v[14:15], off
	v_lshl_add_u64 v[14:15], v[14:15], 0, s[4:5]
	global_load_dword v77, v[14:15], off
	v_lshl_add_u64 v[14:15], v[14:15], 0, s[4:5]
	global_load_dword v78, v[14:15], off
	v_lshl_add_u64 v[14:15], v[14:15], 0, s[4:5]
	global_load_dword v79, v[14:15], off
	v_lshl_add_u64 v[14:15], v[14:15], 0, s[4:5]
	global_load_dword v80, v[14:15], off
	v_lshl_add_u64 v[14:15], v[14:15], 0, s[4:5]
	global_load_dword v81, v[14:15], off
	v_lshl_add_u64 v[14:15], v[14:15], 0, s[4:5]
	global_load_dword v82, v[14:15], off
	v_lshl_add_u64 v[14:15], v[14:15], 0, s[4:5]
	global_load_dword v83, v[14:15], off
	v_lshl_add_u64 v[14:15], v[14:15], 0, s[4:5]
	s_waitcnt vmcnt(56)
; #define LAS __attribute__((address_space(3)))
; __global__ void __launch_bounds__(NWAVES * 64, 2) fwd_megakernel(Args args) {
;     ...
;         for (int e = F.tid; e < D * 16; e += NWAVES * 64) { const int k = e >> 4, j = e & 15; wz[j * D + k] = w_in[(size_t)k * 10256 + 6144 + j]; }
;         __syncthreads();
;         f32x4 gv[8], h0[8], h1[8]; load_gain(args.in[6], F.lane, gv);
;         for (int m = F.gw; m < M; m += 2 * F.NGW) {
;             const int m1 = m + F.NGW; const bool two = m1 < M;
;             row_load(X1B + (size_t)m * D, F.lane, h0);
;             if (two) row_load(X1B + (size_t)m1 * D, F.lane, h1);
;             row_finish(h0, gv, H + (size_t)m * D, F.lane);
;             if (two) row_finish(h1, gv, H + (size_t)m1 * D, F.lane);
;             float mine0 = 0.f, mine1 = 0.f;
; #pragma unroll 1
;             for (int j = 0; j < 16; ++j) {
;                 float a0 = 0.f, a1 = 0.f;
; #pragma unroll
;                 for (int i = 0; i < 8; ++i) { const f32x4 w = *(const LAS f32x4*)(wz + j * D + 256 * i + 4 * F.lane);
;                     a0 += (h0[i].x * w.x + h0[i].y * w.y) + (h0[i].z * w.z + h0[i].w * w.w);
;                     a1 += (h1[i].x * w.x + h1[i].y * w.y) + (h1[i].z * w.z + h1[i].w * w.w); }
;                 a0 = wave_sum(a0); a1 = wave_sum(a1);
;                 if (F.lane == j) { mine0 = a0; mine1 = a1; }
;             }
;             if (F.lane < 16) { BZ[(size_t)m * 16 + F.lane] = mine0; if (two) BZ[(size_t)m1 * 16 + F.lane] = mine1; }
	ds_write_b32 v18, v20 offset:0
	ds_write_b32 v18, v21 offset:128
	ds_write_b32 v18, v22 offset:256
	ds_write_b32 v18, v23 offset:384
	ds_write_b32 v18, v24 offset:512
	ds_write_b32 v18, v25 offset:640
	ds_write_b32 v18, v26 offset:768
	ds_write_b32 v18, v27 offset:896
	s_waitcnt vmcnt(48)
	ds_write_b32 v18, v28 offset:1024
	ds_write_b32 v18, v29 offset:1152
	ds_write_b32 v18, v30 offset:1280
	ds_write_b32 v18, v31 offset:1408
	ds_write_b32 v18, v32 offset:1536
	ds_write_b32 v18, v33 offset:1664
	ds_write_b32 v18, v34 offset:1792
	ds_write_b32 v18, v35 offset:1920
	s_waitcnt vmcnt(40)
	ds_write_b32 v18, v36 offset:2048
	ds_write_b32 v18, v37 offset:2176
	ds_write_b32 v18, v38 offset:2304
	ds_write_b32 v18, v39 offset:2432
	ds_write_b32 v18, v40 offset:2560
	ds_write_b32 v18, v41 offset:2688
	ds_write_b32 v18, v42 offset:2816
	ds_write_b32 v18, v43 offset:2944
	s_waitcnt vmcnt(32)
	ds_write_b32 v18, v44 offset:3072
	ds_write_b32 v18, v45 offset:3200
	ds_write_b32 v18, v46 offset:3328
	ds_write_b32 v18, v47 offset:3456
	ds_write_b32 v18, v48 offset:3584
	ds_write_b32 v18, v49 offset:3712
	ds_write_b32 v18, v50 offset:3840
	ds_write_b32 v18, v51 offset:3968
	s_waitcnt vmcnt(24)
	ds_write_b32 v18, v52 offset:4096
	ds_write_b32 v18, v53 offset:4224
	ds_write_b32 v18, v54 offset:4352
	ds_write_b32 v18, v55 offset:4480
	ds_write_b32 v18, v56 offset:4608
	ds_write_b32 v18, v57 offset:4736
	ds_write_b32 v18, v58 offset:4864
	ds_write_b32 v18, v59 offset:4992
	s_waitcnt vmcnt(16)
	ds_write_b32 v18, v60 offset:5120
	ds_write_b32 v18, v61 offset:5248
	ds_write_b32 v18, v62 offset:5376
	ds_write_b32 v18, v63 offset:5504
	ds_write_b32 v18, v64 offset:5632
	ds_write_b32 v18, v65 offset:5760
	ds_write_b32 v18, v66 offset:5888
	ds_write_b32 v18, v67 offset:6016
	s_waitcnt vmcnt(8)
	ds_write_b32 v18, v68 offset:6144
	ds_write_b32 v18, v69 offset:6272
	ds_write_b32 v18, v70 offset:6400
	ds_write_b32 v18, v71 offset:6528
	ds_write_b32 v18, v72 offset:6656
	ds_write_b32 v18, v73 offset:6784
	ds_write_b32 v18, v74 offset:6912
	ds_write_b32 v18, v75 offset:7040
	s_waitcnt vmcnt(0)
	ds_write_b32 v18, v76 offset:7168
	ds_write_b32 v18, v77 offset:7296
	ds_write_b32 v18, v78 offset:7424
	ds_write_b32 v18, v79 offset:7552
	ds_write_b32 v18, v80 offset:7680
	ds_write_b32 v18, v81 offset:7808
	ds_write_b32 v18, v82 offset:7936
	ds_write_b32 v18, v83 offset:8064
	s_mov_b64 s[0:1], exec
.LBB0_195:
	s_or_b64 exec, exec, s[0:1]
	s_add_u32 s34, s62, 0x100000
	v_cndmask_b32_e64 v0, 0, 1, s[54:55]
	s_addc_u32 s35, s63, 0
	v_cmp_ne_u32_e64 s[56:57], 1, v0
	s_andn2_b64 vcc, exec, s[54:55]
	v_lshlrev_b32_e32 v128, 2, v202
	v_cmp_lt_u32_e64 s[0:1], 47, v202
	s_waitcnt lgkmcnt(0)
	s_barrier
	s_cbranch_vccnz .LBB0_207
	v_mov_b32_e32 v143, 0
	v_lshl_add_u64 v[16:17], s[20:21], 0, v[142:143]
	v_add_co_u32_e32 v28, vcc, 0x1000, v16
	global_load_dwordx4 v[0:3], v142, s[20:21]
	global_load_dwordx4 v[4:7], v142, s[20:21] offset:1024
	global_load_dwordx4 v[8:11], v142, s[20:21] offset:2048
	global_load_dwordx4 v[12:15], v142, s[20:21] offset:3072
	v_addc_co_u32_e32 v29, vcc, 0, v17, vcc
	global_load_dwordx4 v[16:19], v[28:29], off
	global_load_dwordx4 v[20:23], v[28:29], off offset:1024
	global_load_dwordx4 v[24:27], v[28:29], off offset:2048
	s_nop 0
	global_load_dwordx4 v[28:31], v[28:29], off offset:3072
	v_mbcnt_hi_u32_b32 v38, -1, v166
	v_and_b32_e32 v39, 64, v38
	v_add_u32_e32 v39, 64, v39
	v_xor_b32_e32 v40, 1, v38
	v_cmp_lt_i32_e32 vcc, v40, v39
	v_mov_b32_e32 v129, v143
	v_add_u32_e32 v36, 0xffffff40, v128
	v_mov_b32_e32 v37, 0
	v_lshl_add_u64 v[36:37], s[34:35], 0, v[36:37]
	v_cndmask_b32_e32 v40, v38, v40, vcc
	v_lshlrev_b32_e32 v129, 2, v40
	v_xor_b32_e32 v40, 2, v38
	v_cmp_lt_i32_e32 vcc, v40, v39
	v_mov_b32_e32 v141, v143
	v_lshl_add_u64 v[32:33], s[60:61], 0, v[140:141]
	v_cndmask_b32_e32 v40, v38, v40, vcc
	v_lshlrev_b32_e32 v133, 2, v40
	v_xor_b32_e32 v40, 4, v38
	v_cmp_lt_i32_e32 vcc, v40, v39
	v_lshl_add_u64 v[34:35], s[48:49], 0, v[140:141]
	v_lshl_add_u32 v148, v202, 4, 0
	v_cndmask_b32_e32 v40, v38, v40, vcc
	v_lshlrev_b32_e32 v137, 2, v40
	v_xor_b32_e32 v40, 8, v38
	v_cmp_lt_i32_e32 vcc, v40, v39
	s_lshl_b32 s8, s30, 4
	v_add_u32_e32 v149, 0xffffffd0, v202
	v_lshlrev_b32_e32 v149, 13, v149
	v_cndmask_b32_e32 v40, v38, v40, vcc
	v_lshlrev_b32_e32 v141, 2, v40
	v_xor_b32_e32 v40, 16, v38
	v_cmp_lt_i32_e32 vcc, v40, v39
	s_mov_b32 s9, 0xffff0000
	v_mov_b32_e32 v150, 0x358637bd
	v_cndmask_b32_e32 v40, v38, v40, vcc
	v_lshlrev_b32_e32 v146, 2, v40
	v_xor_b32_e32 v40, 32, v38
	v_cmp_lt_i32_e32 vcc, v40, v39
	s_mov_b32 s18, 0xf800000
	v_mov_b32_e32 v151, 0x260
	v_cndmask_b32_e32 v38, v38, v40, vcc
	v_lshlrev_b32_e32 v147, 2, v38
	s_movk_i32 s19, 0x7fff
	s_mov_b32 s12, s68
	v_mov_b32_e32 v38, v143
	v_mov_b32_e32 v39, v143
	v_mov_b32_e32 v40, v143
	v_mov_b32_e32 v41, v143
	v_mov_b32_e32 v42, v143
	v_mov_b32_e32 v43, v143
	v_mov_b32_e32 v44, v143
	v_mov_b32_e32 v45, v143
	v_mov_b32_e32 v46, v143
	v_mov_b32_e32 v47, v143
	v_mov_b32_e32 v48, v143
	v_mov_b32_e32 v49, v143
	v_mov_b32_e32 v50, v143
	v_mov_b32_e32 v51, v143
	v_mov_b32_e32 v52, v143
	v_mov_b32_e32 v53, v143
	v_mov_b32_e32 v54, v143
	v_mov_b32_e32 v55, v143
	v_mov_b32_e32 v56, v143
	v_mov_b32_e32 v57, v143
	v_mov_b32_e32 v58, v143
	v_mov_b32_e32 v59, v143
	v_mov_b32_e32 v60, v143
	v_mov_b32_e32 v61, v143
	v_mov_b32_e32 v62, v143
	v_mov_b32_e32 v63, v143
	v_mov_b32_e32 v64, v143
	v_mov_b32_e32 v65, v143
	v_mov_b32_e32 v66, v143
	v_mov_b32_e32 v67, v143
	v_mov_b32_e32 v68, v143
	v_mov_b32_e32 v69, v143
	s_branch .LBB0_198

; #define LAS __attribute__((address_space(3)))
; __global__ void __launch_bounds__(NWAVES * 64, 2) fwd_megakernel(Args args) {
;     ...
;             for (int j = 0; j < 16; ++j) {
;                 float a0 = 0.f, a1 = 0.f;
; #pragma unroll
;                 for (int i = 0; i < 8; ++i) { const f32x4 w = *(const LAS f32x4*)(wz + j * D + 256 * i + 4 * F.lane);
;                     a0 += (h0[i].x * w.x + h0[i].y * w.y) + (h0[i].z * w.z + h0[i].w * w.w);
;                     a1 += (h1[i].x * w.x + h1[i].y * w.y) + (h1[i].z * w.z + h1[i].w * w.w); }
;                 a0 = wave_sum(a0); a1 = wave_sum(a1);
;                 if (F.lane == j) { mine0 = a0; mine1 = a1; }
;             }
;             if (F.lane < 16) { BZ[(size_t)m * 16 + F.lane] = mine0; if (two) BZ[(size_t)m1 * 16 + F.lane] = mine1; }
.LBB0_203:
	v_add_u32_e32 v153, s6, v148
	ds_read_b128 v[154:157], v153
	ds_read_b128 v[158:161], v153 offset:1024
	ds_read_b128 v[162:165], v153 offset:2048
	ds_read_b128 v[168:171], v153 offset:3072
	ds_read_b128 v[172:175], v153 offset:4096
	ds_read_b128 v[176:179], v153 offset:5120
	ds_read_b128 v[180:183], v153 offset:6144
	ds_read_b128 v[184:187], v153 offset:7168
	s_waitcnt lgkmcnt(7)
	v_pk_mul_f32 v[188:189], v[72:73], v[154:155]
	v_pk_mul_f32 v[190:191], v[70:71], v[156:157]
	s_waitcnt lgkmcnt(6)
	v_pk_mul_f32 v[192:193], v[76:77], v[158:159]
	v_pk_mul_f32 v[194:195], v[74:75], v[160:161]
	v_pk_fma_f32 v[154:155], v[102:103], v[154:155], v[188:189] op_sel:[0,1,0] op_sel_hi:[1,0,1]
	v_pk_fma_f32 v[156:157], v[104:105], v[156:157], v[190:191] op_sel:[0,1,0] op_sel_hi:[1,0,1]
	s_waitcnt lgkmcnt(5)
	v_pk_mul_f32 v[196:197], v[80:81], v[162:163]
	v_pk_mul_f32 v[198:199], v[78:79], v[164:165]
	v_pk_fma_f32 v[158:159], v[106:107], v[158:159], v[192:193] op_sel:[0,1,0] op_sel_hi:[1,0,1]
	v_pk_fma_f32 v[160:161], v[108:109], v[160:161], v[194:195] op_sel:[0,1,0] op_sel_hi:[1,0,1]
	v_pk_add_f32 v[154:155], v[154:155], v[156:157]
	s_waitcnt lgkmcnt(4)
	v_pk_mul_f32 v[204:205], v[84:85], v[168:169]
	v_pk_mul_f32 v[206:207], v[82:83], v[170:171]
	v_pk_fma_f32 v[162:163], v[110:111], v[162:163], v[196:197] op_sel:[0,1,0] op_sel_hi:[1,0,1]
	v_pk_fma_f32 v[164:165], v[112:113], v[164:165], v[198:199] op_sel:[0,1,0] op_sel_hi:[1,0,1]
	v_pk_add_f32 v[156:157], v[158:159], v[160:161]
	v_pk_add_f32 v[154:155], v[154:155], 0 op_sel_hi:[1,0]
	s_waitcnt lgkmcnt(3)
	v_pk_mul_f32 v[208:209], v[88:89], v[172:173]
	v_pk_mul_f32 v[210:211], v[86:87], v[174:175]
	v_pk_fma_f32 v[168:169], v[114:115], v[168:169], v[204:205] op_sel:[0,1,0] op_sel_hi:[1,0,1]
	v_pk_fma_f32 v[170:171], v[116:117], v[170:171], v[206:207] op_sel:[0,1,0] op_sel_hi:[1,0,1]
	v_pk_add_f32 v[158:159], v[162:163], v[164:165]
	v_pk_add_f32 v[154:155], v[154:155], v[156:157]
	s_waitcnt lgkmcnt(2)
	v_pk_mul_f32 v[212:213], v[92:93], v[176:177]
	v_pk_mul_f32 v[214:215], v[90:91], v[178:179]
	v_pk_fma_f32 v[172:173], v[118:119], v[172:173], v[208:209] op_sel:[0,1,0] op_sel_hi:[1,0,1]
	v_pk_fma_f32 v[174:175], v[120:121], v[174:175], v[210:211] op_sel:[0,1,0] op_sel_hi:[1,0,1]
	v_pk_add_f32 v[160:161], v[168:169], v[170:171]
	v_pk_add_f32 v[154:155], v[154:155], v[158:159]
	s_waitcnt lgkmcnt(1)
	v_pk_mul_f32 v[216:217], v[96:97], v[180:181]
	v_pk_mul_f32 v[218:219], v[94:95], v[182:183]
	v_pk_fma_f32 v[176:177], v[122:123], v[176:177], v[212:213] op_sel:[0,1,0] op_sel_hi:[1,0,1]
	v_pk_fma_f32 v[178:179], v[124:125], v[178:179], v[214:215] op_sel:[0,1,0] op_sel_hi:[1,0,1]
	v_pk_add_f32 v[162:163], v[172:173], v[174:175]
	v_pk_add_f32 v[154:155], v[154:155], v[160:161]
	s_waitcnt lgkmcnt(0)
	v_pk_mul_f32 v[220:221], v[100:101], v[184:185]
	v_pk_mul_f32 v[222:223], v[98:99], v[186:187]
	v_pk_fma_f32 v[180:181], v[126:127], v[180:181], v[216:217] op_sel:[0,1,0] op_sel_hi:[1,0,1]
	v_pk_fma_f32 v[182:183], v[130:131], v[182:183], v[218:219] op_sel:[0,1,0] op_sel_hi:[1,0,1]
	v_pk_add_f32 v[164:165], v[176:177], v[178:179]
	v_pk_add_f32 v[154:155], v[154:155], v[162:163]
	v_pk_fma_f32 v[184:185], v[134:135], v[184:185], v[220:221] op_sel:[0,1,0] op_sel_hi:[1,0,1]
	v_pk_fma_f32 v[186:187], v[144:145], v[186:187], v[222:223] op_sel:[0,1,0] op_sel_hi:[1,0,1]
	v_pk_add_f32 v[168:169], v[180:181], v[182:183]
	v_pk_add_f32 v[154:155], v[154:155], v[164:165]
	v_pk_add_f32 v[170:171], v[184:185], v[186:187]
	v_pk_add_f32 v[154:155], v[154:155], v[168:169]
	v_cmp_eq_u32_e32 vcc, s6, v149
	v_pk_add_f32 v[154:155], v[154:155], v[170:171]
	s_addk_i32 s6, 0x2000
	s_cmp_lg_u32 s6, 0x20000
	v_add_f32_dpp v154, v154, v154 quad_perm:[1,0,3,2] row_mask:0xf bank_mask:0xf
	v_add_f32_dpp v155, v155, v155 quad_perm:[1,0,3,2] row_mask:0xf bank_mask:0xf
	s_nop 0
	v_add_f32_dpp v154, v154, v154 quad_perm:[2,3,0,1] row_mask:0xf bank_mask:0xf
	v_add_f32_dpp v155, v155, v155 quad_perm:[2,3,0,1] row_mask:0xf bank_mask:0xf
	s_nop 0
	v_add_f32_dpp v154, v154, v154 row_half_mirror row_mask:0xf bank_mask:0xf
	v_add_f32_dpp v155, v155, v155 row_half_mirror row_mask:0xf bank_mask:0xf
	s_nop 0
	v_add_f32_dpp v154, v154, v154 row_mirror row_mask:0xf bank_mask:0xf
	v_add_f32_dpp v155, v155, v155 row_mirror row_mask:0xf bank_mask:0xf
	s_nop 0
	v_add_f32_dpp v154, v154, v154 row_bcast:15 row_mask:0xa bank_mask:0xf
	v_add_f32_dpp v155, v155, v155 row_bcast:15 row_mask:0xa bank_mask:0xf
	s_nop 0
	v_add_f32_dpp v154, v154, v154 row_bcast:31 row_mask:0xc bank_mask:0xf
	v_add_f32_dpp v155, v155, v155 row_bcast:31 row_mask:0xc bank_mask:0xf
	s_nop 0
	v_cndmask_b32_e32 v152, v152, v154, vcc
	v_cndmask_b32_e32 v143, v143, v155, vcc
	s_cbranch_scc1 .LBB0_203
	s_and_saveexec_b64 s[6:7], s[0:1]
	s_cbranch_execz .LBB0_197
	s_lshl_b64 s[16:17], s[12:13], 6
	v_lshl_add_u64 v[70:71], v[36:37], 0, s[16:17]
	s_and_b64 vcc, exec, s[4:5]
	global_store_dword v[70:71], v152, off
	s_cbranch_vccnz .LBB0_197
	s_ashr_i32 s15, s14, 31
	s_lshl_b64 s[4:5], s[14:15], 6
	v_lshl_add_u64 v[70:71], v[36:37], 0, s[4:5]
	global_store_dword v[70:71], v143, off
	s_branch .LBB0_197

; __global__ void __launch_bounds__(NWAVES * 64, 2) fwd_megakernel(Args args) {
;     ...
;         for (int t = F.gw; t < M; t += F.NGW) {
;             const float pos = (float)positions[t];
;             unsigned* prow = (unsigned*)(QKVA + (size_t)t * 3072) + lane;
;             unsigned wv[16];
; #pragma unroll
;             for (int v = 0; v < 16; ++v) wv[v] = prow[v * 64];
;             float s0 = 0.f, c0 = 1.f, s1 = 0.f, c1 = 1.f;
;             if (lane < 16) {
;                 const int i0 = (2 * lane) & 15;
;                 const float a0 = pos * c_rope_inv[i0], a1 = pos * c_rope_inv[i0 + 1];
;                 const double rv0 = (double)a0 * 0.15915494309189535, rv1 = (double)a1 * 0.15915494309189535;
;                 const float f0 = (float)(rv0 - rint(rv0)), f1 = (float)(rv1 - rint(rv1));
;                 s0 = __builtin_amdgcn_sinf(f0); c0 = __builtin_amdgcn_cosf(f0); s1 = __builtin_amdgcn_sinf(f1); c1 = __builtin_amdgcn_cosf(f1);
;                 if (lane < 8) { s0 = -s0; s1 = -s1; }
;             }
;             const float gq0 = gq[2 * lane], gq1 = gq[2 * lane + 1], gk0 = gk[2 * lane], gk1 = gk[2 * lane + 1];
.LBB0_401:
	s_or_b64 exec, exec, s[0:1]
	s_and_b64 vcc, exec, s[56:57]
	s_waitcnt lgkmcnt(0)
	s_barrier
	s_cbranch_vccnz .LBB0_406
	global_load_dwordx2 v[0:1], v140, s[36:37]
	global_load_dwordx2 v[2:3], v140, s[38:39]
	v_and_b32_e32 v4, 56, v201
	v_mov_b32_e32 v5, 0
	s_getpc_b64 s[4:5]
	s_add_u32 s4, s4, c_rope_inv@rel32@lo+4
	s_addc_u32 s5, s5, c_rope_inv@rel32@hi+12
	v_mbcnt_hi_u32_b32 v8, -1, v166
	v_lshl_add_u64 v[6:7], s[4:5], 0, v[4:5]
	v_and_b32_e32 v4, 64, v8
	v_add_u32_e32 v9, 64, v4
	v_xor_b32_e32 v4, 1, v8
	v_cmp_lt_i32_e32 vcc, v4, v9
	v_xor_b32_e32 v10, 2, v8
	v_xor_b32_e32 v11, 4, v8
	v_cndmask_b32_e32 v4, v8, v4, vcc
	v_cmp_lt_i32_e32 vcc, v10, v9
	s_lshl_b64 s[6:7], s[68:69], 2
	v_xor_b32_e32 v12, 8, v8
	v_cndmask_b32_e32 v10, v8, v10, vcc
	v_cmp_lt_i32_e32 vcc, v11, v9
	s_add_u32 s10, s10, s6
	v_xor_b32_e32 v13, 16, v8
	v_cndmask_b32_e32 v11, v8, v11, vcc
	v_cmp_lt_i32_e32 vcc, v12, v9
	s_addc_u32 s11, s11, s7
	s_ashr_i32 s71, s70, 31
	v_cndmask_b32_e32 v12, v8, v12, vcc
	v_cmp_lt_i32_e32 vcc, v13, v9
	v_xor_b32_e32 v14, 32, v8
	s_lshl_b64 s[12:13], s[70:71], 2
	s_mul_i32 s6, s68, 0x1800
	v_cndmask_b32_e32 v13, v8, v13, vcc
	v_cmp_lt_i32_e32 vcc, v14, v9
	s_mul_hi_i32 s7, s68, 0x1800
	s_add_u32 s6, s62, s6
	v_cndmask_b32_e32 v8, v8, v14, vcc
	v_mov_b32_e32 v129, v5
	s_addc_u32 s7, s63, s7
	v_lshlrev_b32_e32 v14, 2, v8
	v_lshl_add_u64 v[8:9], s[6:7], 0, v[128:129]
	s_mov_b64 s[6:7], 0xbc00f00
	s_mov_b32 s16, 0x6dc9c883
	v_cmp_gt_u32_e64 s[0:1], 16, v202
	v_cmp_gt_u32_e64 s[4:5], 8, v202
	v_lshlrev_b32_e32 v4, 2, v4
	v_lshlrev_b32_e32 v10, 2, v10
	v_lshlrev_b32_e32 v11, 2, v11
	v_lshlrev_b32_e32 v12, 2, v12
	v_lshlrev_b32_e32 v13, 2, v13
	v_lshl_add_u64 v[8:9], v[8:9], 0, s[6:7]
	s_mul_hi_i32 s15, s70, 0x1800
	s_mul_i32 s14, s70, 0x1800
	s_mov_b32 s17, 0x3fc45f30
	s_mov_b32 s8, 0xffff0000
	v_mov_b32_e32 v15, 0x358637bd
	s_mov_b32 s9, 0xf800000
	v_mov_b32_e32 v16, 0x260
	s_movk_i32 s18, 0x7fff
	s_mov_b32 s19, s68
	s_waitcnt vmcnt(0)
	v_mov_b32_e32 v18, 0
	v_mov_b32_e32 v19, 0
	s_and_saveexec_b64 s[6:7], s[0:1]
	global_load_dwordx2 v[18:19], v[6:7], off
	s_or_b64 exec, exec, s[6:7]
	global_load_dword v40, v[8:9], off offset:-3840
	global_load_dword v41, v[8:9], off offset:-3584
	global_load_dword v42, v[8:9], off offset:-3328
	global_load_dword v43, v[8:9], off offset:-3072
	global_load_dword v44, v[8:9], off offset:-2816
	global_load_dword v45, v[8:9], off offset:-2560
	global_load_dword v46, v[8:9], off offset:-2304
	global_load_dword v47, v[8:9], off offset:-2048
	global_load_dword v48, v[8:9], off offset:-1792
	global_load_dword v49, v[8:9], off offset:-1536
	global_load_dword v50, v[8:9], off offset:-1280
	global_load_dword v51, v[8:9], off offset:-1024
	global_load_dword v52, v[8:9], off offset:-768
	global_load_dword v53, v[8:9], off offset:-512
	global_load_dword v54, v[8:9], off offset:-256
	global_load_dword v55, v[8:9], off offset:0
	global_load_dword v56, v5, s[10:11]
	v_mov_b32_e32 v14, 0x3c000000
	s_waitcnt vmcnt(0)
	s_branch .Lp5_body
.Lp5_top:
	s_waitcnt vmcnt(16)
.Lp5_body:
	v_mov_b32_e32 v20, v40
	v_mov_b32_e32 v21, v41
	v_mov_b32_e32 v22, v42
	v_mov_b32_e32 v23, v43
	v_mov_b32_e32 v24, v44
	v_mov_b32_e32 v25, v45
	v_mov_b32_e32 v26, v46
	v_mov_b32_e32 v27, v47
	v_mov_b32_e32 v28, v48
	v_mov_b32_e32 v29, v49
	v_mov_b32_e32 v30, v50
	v_mov_b32_e32 v31, v51
	v_mov_b32_e32 v32, v52
	v_mov_b32_e32 v33, v53
	v_mov_b32_e32 v34, v54
	v_mov_b32_e32 v35, v55
	v_mov_b32_e32 v17, v56
	s_add_i32 s19, s19, s70
	s_add_u32 s10, s10, s12
	s_addc_u32 s11, s11, s13
	v_lshl_add_u64 v[38:39], v[8:9], 0, s[14:15]
	s_cmpk_gt_i32 s19, 0x3fff
	s_cbranch_scc1 .Lp5_nopf
	global_load_dword v40, v[38:39], off offset:-3840
	global_load_dword v41, v[38:39], off offset:-3584
	global_load_dword v42, v[38:39], off offset:-3328
	global_load_dword v43, v[38:39], off offset:-3072
	global_load_dword v44, v[38:39], off offset:-2816
	global_load_dword v45, v[38:39], off offset:-2560
	global_load_dword v46, v[38:39], off offset:-2304
	global_load_dword v47, v[38:39], off offset:-2048
	global_load_dword v48, v[38:39], off offset:-1792
	global_load_dword v49, v[38:39], off offset:-1536
	global_load_dword v50, v[38:39], off offset:-1280
	global_load_dword v51, v[38:39], off offset:-1024
	global_load_dword v52, v[38:39], off offset:-768
	global_load_dword v53, v[38:39], off offset:-512
	global_load_dword v54, v[38:39], off offset:-256
	global_load_dword v55, v[38:39], off offset:0
	global_load_dword v56, v5, s[10:11]
; __device__ __forceinline__ unsigned pk2(float lo, float hi) { return f2bf(lo) | (f2bf(hi) << 16); }
; __global__ void __launch_bounds__(NWAVES * 64, 2) fwd_megakernel(Args args) {
;     ...
;             float s0 = 0.f, c0 = 1.f, s1 = 0.f, c1 = 1.f;
;             if (lane < 16) {
;                 const int i0 = (2 * lane) & 15;
;                 const float a0 = pos * c_rope_inv[i0], a1 = pos * c_rope_inv[i0 + 1];
;                 const double rv0 = (double)a0 * 0.15915494309189535, rv1 = (double)a1 * 0.15915494309189535;
;                 const float f0 = (float)(rv0 - rint(rv0)), f1 = (float)(rv1 - rint(rv1));
;                 s0 = __builtin_amdgcn_sinf(f0); c0 = __builtin_amdgcn_cosf(f0); s1 = __builtin_amdgcn_sinf(f1); c1 = __builtin_amdgcn_cosf(f1);
;                 if (lane < 8) { s0 = -s0; s1 = -s1; }
;             }
;             const float gq0 = gq[2 * lane], gq1 = gq[2 * lane + 1], gk0 = gk[2 * lane], gk1 = gk[2 * lane + 1];
; #pragma unroll
;             for (int v = 0; v < 16; ++v) {
;                 const float x0 = bflo(wv[v]), x1 = bfhi(wv[v]);
;                 const float ss = wave_sum(x0 * x0 + x1 * x1);
;                 const float r = 1.0f / sqrtf(ss * (1.0f / 128.0f) + RMS_EPS);
;                 float y0 = x0 * r * (v < 8 ? gq0 : gk0), y1 = x1 * r * (v < 8 ? gq1 : gk1);
;                 const float p0 = __shfl_xor(y0, 8), p1 = __shfl_xor(y1, 8);
;                 if (lane < 16) { y0 = y0 * c0 + p0 * s0; y1 = y1 * c1 + p1 * s1; }
;                 prow[v * 64] = pk2(y0, y1);
.Lp5_nopf:
	v_mov_b32_e32 v57, 1.0
	v_mov_b32_e32 v58, 0
	v_mov_b32_e32 v59, 1.0
	v_mov_b32_e32 v60, 0
	s_and_saveexec_b64 s[6:7], s[0:1]
	v_cvt_f32_i32_e32 v17, v17
	v_mul_f32_e32 v61, v18, v17
	v_mul_f32_e32 v62, v19, v17
	v_cvt_f64_f32_e32 v[64:65], v61
	v_cvt_f64_f32_e32 v[66:67], v62
	v_mul_f64 v[68:69], v[64:65], s[16:17]
	v_mul_f64 v[70:71], v[66:67], s[16:17]
	v_rndne_f64_e32 v[68:69], v[68:69]
	v_rndne_f64_e32 v[70:71], v[70:71]
	v_fma_f64 v[64:65], v[64:65], s[16:17], -v[68:69]
	v_fma_f64 v[66:67], v[66:67], s[16:17], -v[70:71]
	v_cvt_f32_f64_e32 v61, v[64:65]
	v_cvt_f32_f64_e32 v62, v[66:67]
	v_sin_f32_e32 v58, v61
	v_sin_f32_e32 v60, v62
	v_cos_f32_e32 v57, v61
	v_cos_f32_e32 v59, v62
	s_nop 1
	v_cndmask_b32_e64 v58, v58, -v58, s[4:5]
	v_cndmask_b32_e64 v60, v60, -v60, s[4:5]
	s_or_b64 exec, exec, s[6:7]
	v_lshlrev_b32_e32 v72, 16, v20
	v_and_b32_e32 v73, 0xffff0000, v20
	v_lshlrev_b32_e32 v74, 16, v21
	v_and_b32_e32 v75, 0xffff0000, v21
	v_lshlrev_b32_e32 v76, 16, v22
	v_and_b32_e32 v77, 0xffff0000, v22
	v_lshlrev_b32_e32 v78, 16, v23
	v_and_b32_e32 v79, 0xffff0000, v23
	v_mul_f32_e32 v80, v73, v73
	v_mul_f32_e32 v81, v75, v75
	v_mul_f32_e32 v82, v77, v77
	v_mul_f32_e32 v83, v79, v79
	v_fmac_f32_e32 v80, v72, v72
	v_fmac_f32_e32 v81, v74, v74
	v_fmac_f32_e32 v82, v76, v76
	v_fmac_f32_e32 v83, v78, v78
	v_add_f32_dpp v80, v80, v80 quad_perm:[1,0,3,2] row_mask:0xf bank_mask:0xf
	v_add_f32_dpp v81, v81, v81 quad_perm:[1,0,3,2] row_mask:0xf bank_mask:0xf
	v_add_f32_dpp v82, v82, v82 quad_perm:[1,0,3,2] row_mask:0xf bank_mask:0xf
	v_add_f32_dpp v83, v83, v83 quad_perm:[1,0,3,2] row_mask:0xf bank_mask:0xf
	v_add_f32_dpp v80, v80, v80 quad_perm:[2,3,0,1] row_mask:0xf bank_mask:0xf
	v_add_f32_dpp v81, v81, v81 quad_perm:[2,3,0,1] row_mask:0xf bank_mask:0xf
	v_add_f32_dpp v82, v82, v82 quad_perm:[2,3,0,1] row_mask:0xf bank_mask:0xf
	v_add_f32_dpp v83, v83, v83 quad_perm:[2,3,0,1] row_mask:0xf bank_mask:0xf
	v_add_f32_dpp v80, v80, v80 row_half_mirror row_mask:0xf bank_mask:0xf
	v_add_f32_dpp v81, v81, v81 row_half_mirror row_mask:0xf bank_mask:0xf
	v_add_f32_dpp v82, v82, v82 row_half_mirror row_mask:0xf bank_mask:0xf
	v_add_f32_dpp v83, v83, v83 row_half_mirror row_mask:0xf bank_mask:0xf
	v_add_f32_dpp v80, v80, v80 row_mirror row_mask:0xf bank_mask:0xf
	v_add_f32_dpp v81, v81, v81 row_mirror row_mask:0xf bank_mask:0xf
	v_add_f32_dpp v82, v82, v82 row_mirror row_mask:0xf bank_mask:0xf
	v_add_f32_dpp v83, v83, v83 row_mirror row_mask:0xf bank_mask:0xf
	v_add_f32_dpp v80, v80, v80 row_bcast:15 row_mask:0xa bank_mask:0xf
	v_add_f32_dpp v81, v81, v81 row_bcast:15 row_mask:0xa bank_mask:0xf
	v_add_f32_dpp v82, v82, v82 row_bcast:15 row_mask:0xa bank_mask:0xf
	v_add_f32_dpp v83, v83, v83 row_bcast:15 row_mask:0xa bank_mask:0xf
	v_add_f32_dpp v80, v80, v80 row_bcast:31 row_mask:0xc bank_mask:0xf
	v_add_f32_dpp v81, v81, v81 row_bcast:31 row_mask:0xc bank_mask:0xf
	v_add_f32_dpp v82, v82, v82 row_bcast:31 row_mask:0xc bank_mask:0xf
	v_add_f32_dpp v83, v83, v83 row_bcast:31 row_mask:0xc bank_mask:0xf
	v_readlane_b32 s20, v80, 63
	v_readlane_b32 s21, v81, 63
	v_readlane_b32 s22, v82, 63
	v_readlane_b32 s23, v83, 63
	v_fma_f32 v84, s20, v14, v15
	v_fma_f32 v85, s21, v14, v15
	v_fma_f32 v86, s22, v14, v15
	v_fma_f32 v87, s23, v14, v15
	v_rsq_f32_e32 v84, v84
	v_rsq_f32_e32 v85, v85
	v_rsq_f32_e32 v86, v86
	v_rsq_f32_e32 v87, v87
	v_mul_f32_e32 v72, v72, v84
	v_mul_f32_e32 v73, v73, v84
	v_mul_f32_e32 v74, v74, v85
	v_mul_f32_e32 v75, v75, v85
	v_mul_f32_e32 v76, v76, v86
	v_mul_f32_e32 v77, v77, v86
	v_mul_f32_e32 v78, v78, v87
	v_mul_f32_e32 v79, v79, v87
	v_mul_f32_e32 v72, v72, v0
	v_mul_f32_e32 v73, v73, v1
	v_mul_f32_e32 v74, v74, v0
	v_mul_f32_e32 v75, v75, v1
	v_mul_f32_e32 v76, v76, v0
	v_mul_f32_e32 v77, v77, v1
	v_mul_f32_e32 v78, v78, v0
	v_mul_f32_e32 v79, v79, v1
	v_mov_b32_dpp v88, v72 row_ror:8 row_mask:0xf bank_mask:0xf
	v_mov_b32_dpp v89, v73 row_ror:8 row_mask:0xf bank_mask:0xf
	v_mov_b32_dpp v90, v74 row_ror:8 row_mask:0xf bank_mask:0xf
	v_mov_b32_dpp v91, v75 row_ror:8 row_mask:0xf bank_mask:0xf
	v_mov_b32_dpp v92, v76 row_ror:8 row_mask:0xf bank_mask:0xf
	v_mov_b32_dpp v93, v77 row_ror:8 row_mask:0xf bank_mask:0xf
	v_mov_b32_dpp v94, v78 row_ror:8 row_mask:0xf bank_mask:0xf
	v_mov_b32_dpp v95, v79 row_ror:8 row_mask:0xf bank_mask:0xf
	v_mul_f32_e32 v72, v57, v72
	v_mul_f32_e32 v73, v59, v73
	v_mul_f32_e32 v74, v57, v74
	v_mul_f32_e32 v75, v59, v75
	v_mul_f32_e32 v76, v57, v76
	v_mul_f32_e32 v77, v59, v77
	v_mul_f32_e32 v78, v57, v78
	v_mul_f32_e32 v79, v59, v79
	v_fmac_f32_e32 v72, v58, v88
	v_fmac_f32_e32 v73, v60, v89
	v_fmac_f32_e32 v74, v58, v90
	v_fmac_f32_e32 v75, v60, v91
	v_fmac_f32_e32 v76, v58, v92
	v_fmac_f32_e32 v77, v60, v93
	v_fmac_f32_e32 v78, v58, v94
	v_fmac_f32_e32 v79, v60, v95
	v_cvt_pk_bf16_f32 v80, v72, v73
	v_cvt_pk_bf16_f32 v81, v74, v75
	v_cvt_pk_bf16_f32 v82, v76, v77
	v_cvt_pk_bf16_f32 v83, v78, v79
	global_store_dword v[8:9], v80, off offset:-3840
	global_store_dword v[8:9], v81, off offset:-3584
	global_store_dword v[8:9], v82, off offset:-3328
	global_store_dword v[8:9], v83, off offset:-3072
	v_lshlrev_b32_e32 v72, 16, v24
	v_and_b32_e32 v73, 0xffff0000, v24
	v_lshlrev_b32_e32 v74, 16, v25
	v_and_b32_e32 v75, 0xffff0000, v25
	v_lshlrev_b32_e32 v76, 16, v26
	v_and_b32_e32 v77, 0xffff0000, v26
	v_lshlrev_b32_e32 v78, 16, v27
	v_and_b32_e32 v79, 0xffff0000, v27
	v_mul_f32_e32 v80, v73, v73
	v_mul_f32_e32 v81, v75, v75
	v_mul_f32_e32 v82, v77, v77
	v_mul_f32_e32 v83, v79, v79
	v_fmac_f32_e32 v80, v72, v72
	v_fmac_f32_e32 v81, v74, v74
	v_fmac_f32_e32 v82, v76, v76
	v_fmac_f32_e32 v83, v78, v78
; __device__ __forceinline__ unsigned pk2(float lo, float hi) { return f2bf(lo) | (f2bf(hi) << 16); }
; __global__ void __launch_bounds__(NWAVES * 64, 2) fwd_megakernel(Args args) {
;     ...
;             for (int v = 0; v < 16; ++v) {
;                 const float x0 = bflo(wv[v]), x1 = bfhi(wv[v]);
;                 const float ss = wave_sum(x0 * x0 + x1 * x1);
;                 const float r = 1.0f / sqrtf(ss * (1.0f / 128.0f) + RMS_EPS);
;                 float y0 = x0 * r * (v < 8 ? gq0 : gk0), y1 = x1 * r * (v < 8 ? gq1 : gk1);
;                 const float p0 = __shfl_xor(y0, 8), p1 = __shfl_xor(y1, 8);
;                 if (lane < 16) { y0 = y0 * c0 + p0 * s0; y1 = y1 * c1 + p1 * s1; }
;                 prow[v * 64] = pk2(y0, y1);
	v_add_f32_dpp v80, v80, v80 quad_perm:[1,0,3,2] row_mask:0xf bank_mask:0xf
	v_add_f32_dpp v81, v81, v81 quad_perm:[1,0,3,2] row_mask:0xf bank_mask:0xf
	v_add_f32_dpp v82, v82, v82 quad_perm:[1,0,3,2] row_mask:0xf bank_mask:0xf
	v_add_f32_dpp v83, v83, v83 quad_perm:[1,0,3,2] row_mask:0xf bank_mask:0xf
	v_add_f32_dpp v80, v80, v80 quad_perm:[2,3,0,1] row_mask:0xf bank_mask:0xf
	v_add_f32_dpp v81, v81, v81 quad_perm:[2,3,0,1] row_mask:0xf bank_mask:0xf
	v_add_f32_dpp v82, v82, v82 quad_perm:[2,3,0,1] row_mask:0xf bank_mask:0xf
	v_add_f32_dpp v83, v83, v83 quad_perm:[2,3,0,1] row_mask:0xf bank_mask:0xf
	v_add_f32_dpp v80, v80, v80 row_half_mirror row_mask:0xf bank_mask:0xf
	v_add_f32_dpp v81, v81, v81 row_half_mirror row_mask:0xf bank_mask:0xf
	v_add_f32_dpp v82, v82, v82 row_half_mirror row_mask:0xf bank_mask:0xf
	v_add_f32_dpp v83, v83, v83 row_half_mirror row_mask:0xf bank_mask:0xf
	v_add_f32_dpp v80, v80, v80 row_mirror row_mask:0xf bank_mask:0xf
	v_add_f32_dpp v81, v81, v81 row_mirror row_mask:0xf bank_mask:0xf
	v_add_f32_dpp v82, v82, v82 row_mirror row_mask:0xf bank_mask:0xf
	v_add_f32_dpp v83, v83, v83 row_mirror row_mask:0xf bank_mask:0xf
	v_add_f32_dpp v80, v80, v80 row_bcast:15 row_mask:0xa bank_mask:0xf
	v_add_f32_dpp v81, v81, v81 row_bcast:15 row_mask:0xa bank_mask:0xf
	v_add_f32_dpp v82, v82, v82 row_bcast:15 row_mask:0xa bank_mask:0xf
	v_add_f32_dpp v83, v83, v83 row_bcast:15 row_mask:0xa bank_mask:0xf
	v_add_f32_dpp v80, v80, v80 row_bcast:31 row_mask:0xc bank_mask:0xf
	v_add_f32_dpp v81, v81, v81 row_bcast:31 row_mask:0xc bank_mask:0xf
	v_add_f32_dpp v82, v82, v82 row_bcast:31 row_mask:0xc bank_mask:0xf
	v_add_f32_dpp v83, v83, v83 row_bcast:31 row_mask:0xc bank_mask:0xf
	v_readlane_b32 s20, v80, 63
	v_readlane_b32 s21, v81, 63
	v_readlane_b32 s22, v82, 63
	v_readlane_b32 s23, v83, 63
	v_fma_f32 v84, s20, v14, v15
	v_fma_f32 v85, s21, v14, v15
	v_fma_f32 v86, s22, v14, v15
	v_fma_f32 v87, s23, v14, v15
	v_rsq_f32_e32 v84, v84
	v_rsq_f32_e32 v85, v85
	v_rsq_f32_e32 v86, v86
	v_rsq_f32_e32 v87, v87
	v_mul_f32_e32 v72, v72, v84
	v_mul_f32_e32 v73, v73, v84
	v_mul_f32_e32 v74, v74, v85
	v_mul_f32_e32 v75, v75, v85
	v_mul_f32_e32 v76, v76, v86
	v_mul_f32_e32 v77, v77, v86
	v_mul_f32_e32 v78, v78, v87
	v_mul_f32_e32 v79, v79, v87
	v_mul_f32_e32 v72, v72, v0
	v_mul_f32_e32 v73, v73, v1
	v_mul_f32_e32 v74, v74, v0
	v_mul_f32_e32 v75, v75, v1
	v_mul_f32_e32 v76, v76, v0
	v_mul_f32_e32 v77, v77, v1
	v_mul_f32_e32 v78, v78, v0
	v_mul_f32_e32 v79, v79, v1
	v_mov_b32_dpp v88, v72 row_ror:8 row_mask:0xf bank_mask:0xf
	v_mov_b32_dpp v89, v73 row_ror:8 row_mask:0xf bank_mask:0xf
	v_mov_b32_dpp v90, v74 row_ror:8 row_mask:0xf bank_mask:0xf
	v_mov_b32_dpp v91, v75 row_ror:8 row_mask:0xf bank_mask:0xf
	v_mov_b32_dpp v92, v76 row_ror:8 row_mask:0xf bank_mask:0xf
	v_mov_b32_dpp v93, v77 row_ror:8 row_mask:0xf bank_mask:0xf
	v_mov_b32_dpp v94, v78 row_ror:8 row_mask:0xf bank_mask:0xf
	v_mov_b32_dpp v95, v79 row_ror:8 row_mask:0xf bank_mask:0xf
	v_mul_f32_e32 v72, v57, v72
	v_mul_f32_e32 v73, v59, v73
	v_mul_f32_e32 v74, v57, v74
	v_mul_f32_e32 v75, v59, v75
	v_mul_f32_e32 v76, v57, v76
	v_mul_f32_e32 v77, v59, v77
	v_mul_f32_e32 v78, v57, v78
	v_mul_f32_e32 v79, v59, v79
	v_fmac_f32_e32 v72, v58, v88
	v_fmac_f32_e32 v73, v60, v89
	v_fmac_f32_e32 v74, v58, v90
	v_fmac_f32_e32 v75, v60, v91
	v_fmac_f32_e32 v76, v58, v92
	v_fmac_f32_e32 v77, v60, v93
	v_fmac_f32_e32 v78, v58, v94
	v_fmac_f32_e32 v79, v60, v95
	v_cvt_pk_bf16_f32 v80, v72, v73
	v_cvt_pk_bf16_f32 v81, v74, v75
	v_cvt_pk_bf16_f32 v82, v76, v77
	v_cvt_pk_bf16_f32 v83, v78, v79
	global_store_dword v[8:9], v80, off offset:-2816
	global_store_dword v[8:9], v81, off offset:-2560
	global_store_dword v[8:9], v82, off offset:-2304
	global_store_dword v[8:9], v83, off offset:-2048
	v_lshlrev_b32_e32 v72, 16, v28
	v_and_b32_e32 v73, 0xffff0000, v28
	v_lshlrev_b32_e32 v74, 16, v29
	v_and_b32_e32 v75, 0xffff0000, v29
	v_lshlrev_b32_e32 v76, 16, v30
	v_and_b32_e32 v77, 0xffff0000, v30
	v_lshlrev_b32_e32 v78, 16, v31
	v_and_b32_e32 v79, 0xffff0000, v31
	v_mul_f32_e32 v80, v73, v73
	v_mul_f32_e32 v81, v75, v75
	v_mul_f32_e32 v82, v77, v77
	v_mul_f32_e32 v83, v79, v79
	v_fmac_f32_e32 v80, v72, v72
	v_fmac_f32_e32 v81, v74, v74
	v_fmac_f32_e32 v82, v76, v76
	v_fmac_f32_e32 v83, v78, v78
	v_add_f32_dpp v80, v80, v80 quad_perm:[1,0,3,2] row_mask:0xf bank_mask:0xf
	v_add_f32_dpp v81, v81, v81 quad_perm:[1,0,3,2] row_mask:0xf bank_mask:0xf
	v_add_f32_dpp v82, v82, v82 quad_perm:[1,0,3,2] row_mask:0xf bank_mask:0xf
	v_add_f32_dpp v83, v83, v83 quad_perm:[1,0,3,2] row_mask:0xf bank_mask:0xf
	v_add_f32_dpp v80, v80, v80 quad_perm:[2,3,0,1] row_mask:0xf bank_mask:0xf
	v_add_f32_dpp v81, v81, v81 quad_perm:[2,3,0,1] row_mask:0xf bank_mask:0xf
	v_add_f32_dpp v82, v82, v82 quad_perm:[2,3,0,1] row_mask:0xf bank_mask:0xf
	v_add_f32_dpp v83, v83, v83 quad_perm:[2,3,0,1] row_mask:0xf bank_mask:0xf
	v_add_f32_dpp v80, v80, v80 row_half_mirror row_mask:0xf bank_mask:0xf
	v_add_f32_dpp v81, v81, v81 row_half_mirror row_mask:0xf bank_mask:0xf
	v_add_f32_dpp v82, v82, v82 row_half_mirror row_mask:0xf bank_mask:0xf
	v_add_f32_dpp v83, v83, v83 row_half_mirror row_mask:0xf bank_mask:0xf
	v_add_f32_dpp v80, v80, v80 row_mirror row_mask:0xf bank_mask:0xf
	v_add_f32_dpp v81, v81, v81 row_mirror row_mask:0xf bank_mask:0xf
	v_add_f32_dpp v82, v82, v82 row_mirror row_mask:0xf bank_mask:0xf
	v_add_f32_dpp v83, v83, v83 row_mirror row_mask:0xf bank_mask:0xf
	v_add_f32_dpp v80, v80, v80 row_bcast:15 row_mask:0xa bank_mask:0xf
	v_add_f32_dpp v81, v81, v81 row_bcast:15 row_mask:0xa bank_mask:0xf
; __device__ __forceinline__ unsigned pk2(float lo, float hi) { return f2bf(lo) | (f2bf(hi) << 16); }
; __global__ void __launch_bounds__(NWAVES * 64, 2) fwd_megakernel(Args args) {
;     ...
;             for (int v = 0; v < 16; ++v) {
;                 const float x0 = bflo(wv[v]), x1 = bfhi(wv[v]);
;                 const float ss = wave_sum(x0 * x0 + x1 * x1);
;                 const float r = 1.0f / sqrtf(ss * (1.0f / 128.0f) + RMS_EPS);
;                 float y0 = x0 * r * (v < 8 ? gq0 : gk0), y1 = x1 * r * (v < 8 ? gq1 : gk1);
;                 const float p0 = __shfl_xor(y0, 8), p1 = __shfl_xor(y1, 8);
;                 if (lane < 16) { y0 = y0 * c0 + p0 * s0; y1 = y1 * c1 + p1 * s1; }
;                 prow[v * 64] = pk2(y0, y1);
;             }
	v_add_f32_dpp v82, v82, v82 row_bcast:15 row_mask:0xa bank_mask:0xf
	v_add_f32_dpp v83, v83, v83 row_bcast:15 row_mask:0xa bank_mask:0xf
	v_add_f32_dpp v80, v80, v80 row_bcast:31 row_mask:0xc bank_mask:0xf
	v_add_f32_dpp v81, v81, v81 row_bcast:31 row_mask:0xc bank_mask:0xf
	v_add_f32_dpp v82, v82, v82 row_bcast:31 row_mask:0xc bank_mask:0xf
	v_add_f32_dpp v83, v83, v83 row_bcast:31 row_mask:0xc bank_mask:0xf
	v_readlane_b32 s20, v80, 63
	v_readlane_b32 s21, v81, 63
	v_readlane_b32 s22, v82, 63
	v_readlane_b32 s23, v83, 63
	v_fma_f32 v84, s20, v14, v15
	v_fma_f32 v85, s21, v14, v15
	v_fma_f32 v86, s22, v14, v15
	v_fma_f32 v87, s23, v14, v15
	v_rsq_f32_e32 v84, v84
	v_rsq_f32_e32 v85, v85
	v_rsq_f32_e32 v86, v86
	v_rsq_f32_e32 v87, v87
	v_mul_f32_e32 v72, v72, v84
	v_mul_f32_e32 v73, v73, v84
	v_mul_f32_e32 v74, v74, v85
	v_mul_f32_e32 v75, v75, v85
	v_mul_f32_e32 v76, v76, v86
	v_mul_f32_e32 v77, v77, v86
	v_mul_f32_e32 v78, v78, v87
	v_mul_f32_e32 v79, v79, v87
	v_mul_f32_e32 v72, v72, v2
	v_mul_f32_e32 v73, v73, v3
	v_mul_f32_e32 v74, v74, v2
	v_mul_f32_e32 v75, v75, v3
	v_mul_f32_e32 v76, v76, v2
	v_mul_f32_e32 v77, v77, v3
	v_mul_f32_e32 v78, v78, v2
	v_mul_f32_e32 v79, v79, v3
	v_mov_b32_dpp v88, v72 row_ror:8 row_mask:0xf bank_mask:0xf
	v_mov_b32_dpp v89, v73 row_ror:8 row_mask:0xf bank_mask:0xf
	v_mov_b32_dpp v90, v74 row_ror:8 row_mask:0xf bank_mask:0xf
	v_mov_b32_dpp v91, v75 row_ror:8 row_mask:0xf bank_mask:0xf
	v_mov_b32_dpp v92, v76 row_ror:8 row_mask:0xf bank_mask:0xf
	v_mov_b32_dpp v93, v77 row_ror:8 row_mask:0xf bank_mask:0xf
	v_mov_b32_dpp v94, v78 row_ror:8 row_mask:0xf bank_mask:0xf
	v_mov_b32_dpp v95, v79 row_ror:8 row_mask:0xf bank_mask:0xf
	v_mul_f32_e32 v72, v57, v72
	v_mul_f32_e32 v73, v59, v73
	v_mul_f32_e32 v74, v57, v74
	v_mul_f32_e32 v75, v59, v75
	v_mul_f32_e32 v76, v57, v76
	v_mul_f32_e32 v77, v59, v77
	v_mul_f32_e32 v78, v57, v78
	v_mul_f32_e32 v79, v59, v79
	v_fmac_f32_e32 v72, v58, v88
	v_fmac_f32_e32 v73, v60, v89
	v_fmac_f32_e32 v74, v58, v90
	v_fmac_f32_e32 v75, v60, v91
	v_fmac_f32_e32 v76, v58, v92
	v_fmac_f32_e32 v77, v60, v93
	v_fmac_f32_e32 v78, v58, v94
	v_fmac_f32_e32 v79, v60, v95
	v_cvt_pk_bf16_f32 v80, v72, v73
	v_cvt_pk_bf16_f32 v81, v74, v75
	v_cvt_pk_bf16_f32 v82, v76, v77
	v_cvt_pk_bf16_f32 v83, v78, v79
	global_store_dword v[8:9], v80, off offset:-1792
	global_store_dword v[8:9], v81, off offset:-1536
	global_store_dword v[8:9], v82, off offset:-1280
	global_store_dword v[8:9], v83, off offset:-1024
	v_lshlrev_b32_e32 v72, 16, v32
	v_and_b32_e32 v73, 0xffff0000, v32
	v_lshlrev_b32_e32 v74, 16, v33
	v_and_b32_e32 v75, 0xffff0000, v33
	v_lshlrev_b32_e32 v76, 16, v34
	v_and_b32_e32 v77, 0xffff0000, v34
	v_lshlrev_b32_e32 v78, 16, v35
	v_and_b32_e32 v79, 0xffff0000, v35
	v_mul_f32_e32 v80, v73, v73
	v_mul_f32_e32 v81, v75, v75
	v_mul_f32_e32 v82, v77, v77
	v_mul_f32_e32 v83, v79, v79
	v_fmac_f32_e32 v80, v72, v72
	v_fmac_f32_e32 v81, v74, v74
	v_fmac_f32_e32 v82, v76, v76
	v_fmac_f32_e32 v83, v78, v78
	v_add_f32_dpp v80, v80, v80 quad_perm:[1,0,3,2] row_mask:0xf bank_mask:0xf
	v_add_f32_dpp v81, v81, v81 quad_perm:[1,0,3,2] row_mask:0xf bank_mask:0xf
	v_add_f32_dpp v82, v82, v82 quad_perm:[1,0,3,2] row_mask:0xf bank_mask:0xf
	v_add_f32_dpp v83, v83, v83 quad_perm:[1,0,3,2] row_mask:0xf bank_mask:0xf
	v_add_f32_dpp v80, v80, v80 quad_perm:[2,3,0,1] row_mask:0xf bank_mask:0xf
	v_add_f32_dpp v81, v81, v81 quad_perm:[2,3,0,1] row_mask:0xf bank_mask:0xf
	v_add_f32_dpp v82, v82, v82 quad_perm:[2,3,0,1] row_mask:0xf bank_mask:0xf
	v_add_f32_dpp v83, v83, v83 quad_perm:[2,3,0,1] row_mask:0xf bank_mask:0xf
	v_add_f32_dpp v80, v80, v80 row_half_mirror row_mask:0xf bank_mask:0xf
	v_add_f32_dpp v81, v81, v81 row_half_mirror row_mask:0xf bank_mask:0xf
	v_add_f32_dpp v82, v82, v82 row_half_mirror row_mask:0xf bank_mask:0xf
	v_add_f32_dpp v83, v83, v83 row_half_mirror row_mask:0xf bank_mask:0xf
	v_add_f32_dpp v80, v80, v80 row_mirror row_mask:0xf bank_mask:0xf
	v_add_f32_dpp v81, v81, v81 row_mirror row_mask:0xf bank_mask:0xf
	v_add_f32_dpp v82, v82, v82 row_mirror row_mask:0xf bank_mask:0xf
	v_add_f32_dpp v83, v83, v83 row_mirror row_mask:0xf bank_mask:0xf
	v_add_f32_dpp v80, v80, v80 row_bcast:15 row_mask:0xa bank_mask:0xf
	v_add_f32_dpp v81, v81, v81 row_bcast:15 row_mask:0xa bank_mask:0xf
	v_add_f32_dpp v82, v82, v82 row_bcast:15 row_mask:0xa bank_mask:0xf
	v_add_f32_dpp v83, v83, v83 row_bcast:15 row_mask:0xa bank_mask:0xf
	v_add_f32_dpp v80, v80, v80 row_bcast:31 row_mask:0xc bank_mask:0xf
	v_add_f32_dpp v81, v81, v81 row_bcast:31 row_mask:0xc bank_mask:0xf
	v_add_f32_dpp v82, v82, v82 row_bcast:31 row_mask:0xc bank_mask:0xf
	v_add_f32_dpp v83, v83, v83 row_bcast:31 row_mask:0xc bank_mask:0xf
	v_readlane_b32 s20, v80, 63
	v_readlane_b32 s21, v81, 63
	v_readlane_b32 s22, v82, 63
	v_readlane_b32 s23, v83, 63
	v_fma_f32 v84, s20, v14, v15
	v_fma_f32 v85, s21, v14, v15
	v_fma_f32 v86, s22, v14, v15
	v_fma_f32 v87, s23, v14, v15
	v_rsq_f32_e32 v84, v84
	v_rsq_f32_e32 v85, v85
	v_rsq_f32_e32 v86, v86
	v_rsq_f32_e32 v87, v87
	v_mul_f32_e32 v72, v72, v84
	v_mul_f32_e32 v73, v73, v84
	v_mul_f32_e32 v74, v74, v85
	v_mul_f32_e32 v75, v75, v85
	v_mul_f32_e32 v76, v76, v86
	v_mul_f32_e32 v77, v77, v86
	v_mul_f32_e32 v78, v78, v87
	v_mul_f32_e32 v79, v79, v87
	v_mul_f32_e32 v72, v72, v2
	v_mul_f32_e32 v73, v73, v3
	v_mul_f32_e32 v74, v74, v2
	v_mul_f32_e32 v75, v75, v3
	v_mul_f32_e32 v76, v76, v2
	v_mul_f32_e32 v77, v77, v3
	v_mul_f32_e32 v78, v78, v2
	v_mul_f32_e32 v79, v79, v3
	v_mov_b32_dpp v88, v72 row_ror:8 row_mask:0xf bank_mask:0xf
	v_mov_b32_dpp v89, v73 row_ror:8 row_mask:0xf bank_mask:0xf
	v_mov_b32_dpp v90, v74 row_ror:8 row_mask:0xf bank_mask:0xf
	v_mov_b32_dpp v91, v75 row_ror:8 row_mask:0xf bank_mask:0xf
	v_mov_b32_dpp v92, v76 row_ror:8 row_mask:0xf bank_mask:0xf
	v_mov_b32_dpp v93, v77 row_ror:8 row_mask:0xf bank_mask:0xf
	v_mov_b32_dpp v94, v78 row_ror:8 row_mask:0xf bank_mask:0xf
	v_mov_b32_dpp v95, v79 row_ror:8 row_mask:0xf bank_mask:0xf
	v_mul_f32_e32 v72, v57, v72
	v_mul_f32_e32 v73, v59, v73
	v_mul_f32_e32 v74, v57, v74
	v_mul_f32_e32 v75, v59, v75
	v_mul_f32_e32 v76, v57, v76
	v_mul_f32_e32 v77, v59, v77
	v_mul_f32_e32 v78, v57, v78
	v_mul_f32_e32 v79, v59, v79
	v_fmac_f32_e32 v72, v58, v88
	v_fmac_f32_e32 v73, v60, v89
	v_fmac_f32_e32 v74, v58, v90
	v_fmac_f32_e32 v75, v60, v91
	v_fmac_f32_e32 v76, v58, v92
	v_fmac_f32_e32 v77, v60, v93
	v_fmac_f32_e32 v78, v58, v94
	v_fmac_f32_e32 v79, v60, v95
	v_cvt_pk_bf16_f32 v80, v72, v73
	v_cvt_pk_bf16_f32 v81, v74, v75
	v_cvt_pk_bf16_f32 v82, v76, v77
	v_cvt_pk_bf16_f32 v83, v78, v79
	global_store_dword v[8:9], v80, off offset:-768
	global_store_dword v[8:9], v81, off offset:-512
	global_store_dword v[8:9], v82, off offset:-256
	global_store_dword v[8:9], v83, off offset:0
	v_mov_b32_e32 v8, v38
	v_mov_b32_e32 v9, v39
	s_cmpk_gt_i32 s19, 0x3fff
	s_cbranch_scc0 .Lp5_top
